# branch-GEMM phase stagger in four groups (bid&3)*3us instead of odd workgroups 6us
# speedup vs baseline: 1.0030x; 1.0030x over previous
.LBB0_779:
	s_cmp_le_i32 s76, s18
	s_cselect_b64 s[0:1], -1, 0
	s_and_b64 s[2:3], s[0:1], s[4:5]
	v_readlane_b32 s0, v236, 1
	s_mul_i32 s0, s0, 7
	s_add_i32 s29, s0, 6
	s_cmp_lt_i32 s29, s77
	s_cselect_b64 s[0:1], -1, 0
	s_andn2_b64 vcc, exec, s[2:3]
	s_cbranch_vccnz .LBB0_920
	v_readlane_b32 s98, v237, 48
	s_and_b32 s98, s98, 3
	s_cmp_eq_u32 s98, 0
	s_cbranch_scc1 .Lstg_skipp
	s_mulk_i32 s98, 0x12c
	s_mov_b32 s101, s98
	s_memrealtime s[98:99]
	s_waitcnt lgkmcnt(0)
	s_add_u32 s100, s98, s101
